# exp_ssmlast
# baseline (speedup 1.0000x reference)
; __device__ __forceinline__ void phase_mixers(const Params& p, int cidx, int layer) {
;     ...
;   for (;;) {
;     const int tidx = opaque_tid();
;     const int wid = tidx >> 6;
;     __syncthreads();
;     if (tidx == 0) s_item = atomicAdd(ctr, 1);
;     __syncthreads();
;     const int it = s_item;
;     if (it >= N_SSM + N_POOL + N_ATT + n_cv) break;
;     if (it < N_SSM) ssm_item(p, layer, it & 127, tidx);
;     else if (it < N_SSM + N_POOL) pool_block_item(p, layer, (it - N_SSM) & 255, tidx);
;     else if (it < N_SSM + N_POOL + N_ATT) attn_wave_item(p, ((it - N_SSM - N_POOL) & 511) * 8 + wid, tidx);
;     else cv_item_B(p, (it - N_SSM - N_POOL - N_ATT) % CV_B, tidx);
.LBB0_77:
	s_or_b64 exec, exec, s[6:7]
	s_waitcnt lgkmcnt(0)
	s_barrier
	ds_read_b32 v0, v163 offset:20
	s_mov_b64 s[6:7], -1
	s_waitcnt lgkmcnt(0)
	v_cmp_le_i32_e32 vcc, s65, v0
	v_readfirstlane_b32 s64, v0
	s_cbranch_vccnz .LBB0_72
	v_ashrrev_i32_e32 v97, 6, v164
	s_cmp_lt_u32 s64, 0x380
	s_cbranch_scc0 .Lsl_done
	s_cmp_lt_u32 s64, 0x300
	s_cbranch_scc1 .Lsl_pa
	s_sub_u32 s64, s64, 0x300
	s_branch .Lsl_done
.Lsl_pa:
	s_add_u32 s64, s64, 0x80
